# DeltaNet chunkwise WY form on f32 matrix cores: state-update stage waits for all its LDS reads at once (no counted wait over reads above and below 64 KB)
# speedup vs baseline: 1.0010x; 1.0010x over previous
.Ldc_s4w:
	s_and_b32 s61, s60, 1
	s_lshl_b32 s61, s61, 6
	v_mul_u32_u24_e32 v244, 0x480, v223
	v_lshl_add_u32 v244, v222, 2, v244
	v_add_u32_e32 v244, s61, v244
	ds_read_b32 v34, v244 offset:57856
	ds_read_b32 v35, v244 offset:58000
	ds_read_b32 v36, v244 offset:58144
	ds_read_b32 v37, v244 offset:58288
	ds_read_b32 v38, v244 offset:58432
	ds_read_b32 v39, v244 offset:58576
	ds_read_b32 v40, v244 offset:58720
	ds_read_b32 v41, v244 offset:58864
	v_lshlrev_b32_e32 v245, 5, v223
	v_add_u32_e32 v245, 0x13780, v245
	ds_read_b128 v[42:45], v245
	ds_read_b128 v[46:49], v245 offset:16
	v_mov_b32_e32 v79, 0x1377c
	ds_read_b32 v78, v79
	v_mul_u32_u24_e32 v246, 0x880, v223
	v_lshl_add_u32 v246, v222, 2, v246
	s_and_b32 s61, s60, 1
	s_lshl_b32 s61, s61, 6
	s_add_i32 s61, s61, 0x11600
	v_mul_u32_u24_e32 v244, 0x210, v223
	v_lshl_add_u32 v244, v222, 2, v244
	v_add_u32_e32 v244, s61, v244
	ds_read_b32 v26, v246 offset:8704
	ds_read_b32 v27, v246 offset:8976
	ds_read_b32 v28, v246 offset:9248
	ds_read_b32 v29, v246 offset:9520
	ds_read_b32 v30, v246 offset:9792
	ds_read_b32 v31, v246 offset:10064
	ds_read_b32 v32, v246 offset:10336
	ds_read_b32 v33, v246 offset:10608
	ds_read_b32 v66, v244 offset:0
	ds_read_b32 v67, v244 offset:132
	ds_read_b32 v68, v244 offset:264
	ds_read_b32 v69, v244 offset:396
	ds_read_b32 v50, v246 offset:8768
	ds_read_b32 v51, v246 offset:9040
	ds_read_b32 v52, v246 offset:9312
	ds_read_b32 v53, v246 offset:9584
	ds_read_b32 v54, v246 offset:9856
	ds_read_b32 v55, v246 offset:10128
	ds_read_b32 v56, v246 offset:10400
	ds_read_b32 v57, v246 offset:10672
	ds_read_b32 v70, v244 offset:2112
	ds_read_b32 v71, v244 offset:2244
	ds_read_b32 v72, v244 offset:2376
	ds_read_b32 v73, v244 offset:2508
	ds_read_b32 v58, v246 offset:8832
	ds_read_b32 v59, v246 offset:9104
	ds_read_b32 v60, v246 offset:9376
	ds_read_b32 v61, v246 offset:9648
	ds_read_b32 v62, v246 offset:9920
	ds_read_b32 v63, v246 offset:10192
	ds_read_b32 v64, v246 offset:10464
	ds_read_b32 v65, v246 offset:10736
	ds_read_b32 v74, v244 offset:4224
	ds_read_b32 v75, v244 offset:4356
	ds_read_b32 v76, v244 offset:4488
	ds_read_b32 v77, v244 offset:4620
	s_waitcnt lgkmcnt(0)
	v_mul_f32_e32 v26, v42, v26
	v_mul_f32_e32 v27, v43, v27
	v_mul_f32_e32 v28, v44, v28
	v_mul_f32_e32 v29, v45, v29
	v_mul_f32_e32 v30, v46, v30
	v_mul_f32_e32 v31, v47, v31
	v_mul_f32_e32 v32, v48, v32
	v_mul_f32_e32 v33, v49, v33
	v_mul_f32_e32 v66, v78, v66
	v_mul_f32_e32 v67, v78, v67
	v_mul_f32_e32 v68, v78, v68
	v_mul_f32_e32 v69, v78, v69
	s_nop 1
	v_mfma_f32_16x16x4_f32 v[66:69], v26, v34, v[66:69]
	v_mfma_f32_16x16x4_f32 v[66:69], v27, v35, v[66:69]
	v_mfma_f32_16x16x4_f32 v[66:69], v28, v36, v[66:69]
	v_mfma_f32_16x16x4_f32 v[66:69], v29, v37, v[66:69]
	v_mfma_f32_16x16x4_f32 v[66:69], v30, v38, v[66:69]
	v_mfma_f32_16x16x4_f32 v[66:69], v31, v39, v[66:69]
	v_mfma_f32_16x16x4_f32 v[66:69], v32, v40, v[66:69]
	v_mfma_f32_16x16x4_f32 v[66:69], v33, v41, v[66:69]
	v_mul_f32_e32 v50, v42, v50
	v_mul_f32_e32 v51, v43, v51
	v_mul_f32_e32 v52, v44, v52
	v_mul_f32_e32 v53, v45, v53
	v_mul_f32_e32 v54, v46, v54
	v_mul_f32_e32 v55, v47, v55
	v_mul_f32_e32 v56, v48, v56
	v_mul_f32_e32 v57, v49, v57
	v_mul_f32_e32 v70, v78, v70
	v_mul_f32_e32 v71, v78, v71
	v_mul_f32_e32 v72, v78, v72
	v_mul_f32_e32 v73, v78, v73
	s_nop 1
	v_mfma_f32_16x16x4_f32 v[70:73], v50, v34, v[70:73]
	v_mfma_f32_16x16x4_f32 v[70:73], v51, v35, v[70:73]
	v_mfma_f32_16x16x4_f32 v[70:73], v52, v36, v[70:73]
	v_mfma_f32_16x16x4_f32 v[70:73], v53, v37, v[70:73]
	v_mfma_f32_16x16x4_f32 v[70:73], v54, v38, v[70:73]
	v_mfma_f32_16x16x4_f32 v[70:73], v55, v39, v[70:73]
	v_mfma_f32_16x16x4_f32 v[70:73], v56, v40, v[70:73]
	v_mfma_f32_16x16x4_f32 v[70:73], v57, v41, v[70:73]
	v_mul_f32_e32 v58, v42, v58
	v_mul_f32_e32 v59, v43, v59
	v_mul_f32_e32 v60, v44, v60
	v_mul_f32_e32 v61, v45, v61
	v_mul_f32_e32 v62, v46, v62
	v_mul_f32_e32 v63, v47, v63
	v_mul_f32_e32 v64, v48, v64
	v_mul_f32_e32 v65, v49, v65
	v_mul_f32_e32 v74, v78, v74
	v_mul_f32_e32 v75, v78, v75
	v_mul_f32_e32 v76, v78, v76
	v_mul_f32_e32 v77, v78, v77
	s_nop 1
	v_mfma_f32_16x16x4_f32 v[74:77], v58, v34, v[74:77]
	v_mfma_f32_16x16x4_f32 v[74:77], v59, v35, v[74:77]
	v_mfma_f32_16x16x4_f32 v[74:77], v60, v36, v[74:77]
	v_mfma_f32_16x16x4_f32 v[74:77], v61, v37, v[74:77]
	v_mfma_f32_16x16x4_f32 v[74:77], v62, v38, v[74:77]
	v_mfma_f32_16x16x4_f32 v[74:77], v63, v39, v[74:77]
	v_mfma_f32_16x16x4_f32 v[74:77], v64, v40, v[74:77]
	v_mfma_f32_16x16x4_f32 v[74:77], v65, v41, v[74:77]
	s_nop 7
	s_nop 3
	ds_write_b32 v244, v66 offset:0
	ds_write_b32 v244, v67 offset:132
	ds_write_b32 v244, v68 offset:264
	ds_write_b32 v244, v69 offset:396
	ds_write_b32 v244, v70 offset:2112
	ds_write_b32 v244, v71 offset:2244
	ds_write_b32 v244, v72 offset:2376
	ds_write_b32 v244, v73 offset:2508
	ds_write_b32 v244, v74 offset:4224
	ds_write_b32 v244, v75 offset:4356
	ds_write_b32 v244, v76 offset:4488
	ds_write_b32 v244, v77 offset:4620
